# SWA band loop: depth-2 K/V prefetch (second staging register set v160-175, chunk c+2 issued after chunk c image is written, counted vmcnt(4), clamped rows + zero fix-up instead of exec-masked loads)
# baseline (speedup 1.0000x reference)
; #define LAS __attribute__((address_space(3)))
; template <int HD, int DV, int HW, int MODE> ...
;     ...
;     int tid = threadIdx.x; asm volatile("" : "+v"(tid));
;     const int w = __builtin_amdgcn_readfirstlane(tid >> 6), lane = tid & 63, ql = lane & 31, hh = lane >> 5;
;     const int iw = i0 + 32 * w, x32a = ((lane ^ 32) << 2);
;     LAS unsigned char* Kl = lds; LAS unsigned char* Vl = lds + KB;
;     bf16x8 qf[KS];
;     { const bf16_t* qrow = qp + (tok0 + (size_t)r * (iw + ql)) * ld + 8 * hh;
; #pragma unroll
;       for (int ks = 0; ks < KS; ++ks) qf[ks] = *(const bf16x8*)(qrow + 16 * ks); }
;     f32x16 O[NTV];
; #pragma unroll
;     for (int t = 0; t < NTV; ++t)
; #pragma unroll
;         for (int i = 0; i < 16; ++i) O[t][i] = 0.f;
;     float m = (MODE == 1) ? sink2 : -1e30f, l = (MODE == 1 && hh == 0) ? 1.0f : 0.f;
;     const int pi = (ql & ~12) | ((ql & 4) << 1) | ((ql & 8) >> 1);
;     const LAS unsigned char* kread = Kl + pi * RSK + 16 * hh;
;     const int g16 = lane >> 4, i16 = lane & 15;
;     const LAS unsigned char* vread = Vl + (8 * (g16 >> 1) + (i16 >> 2)) * RSV + (16 * (g16 & 1) + 4 * (i16 & 3)) * 2;
;     u32x4 kreg[KLD], vreg[VLD];
;     auto prefetch = [&](int c) {
;         const int jc = i0 - HW + CR * c;
; #pragma unroll
;         for (int i = 0; i < KLD; ++i) { const int idx = tid + 512 * i, row = idx / KCH, ch = idx % KCH, j = jc + row;
;             kreg[i] = (j >= 0 && j < L) ? *(const u32x4*)(kp + (tok0 + (size_t)r * j) * ld + ch * 8) : (u32x4){0, 0, 0, 0}; }
; #pragma unroll
;         for (int i = 0; i < VLD; ++i) { const int idx = tid + 512 * i, row = idx / VCH, ch = idx % VCH, j = jc + row;
;             vreg[i] = (j >= 0 && j < L) ? *(const u32x4*)(vp + (tok0 + (size_t)r * j) * ld + ch * 8) : (u32x4){0, 0, 0, 0}; }
;     };
;     prefetch(0);
.LBB0_168:
	s_or_b64 exec, exec, s[40:41]
	v_and_b32_e32 v13, 63, v6
	v_lshlrev_b32_e32 v100, 3, v10
	v_cmp_gt_u32_e32 vcc, 32, v13
	v_lshlrev_b32_e32 v10, 1, v6
	v_lshrrev_b32_e32 v13, 1, v6
	s_waitcnt vmcnt(0)
	v_mul_f32_e32 v115, 0x3fb8aa3b, v8
	v_and_b32_e32 v8, 19, v6
	v_and_b32_e32 v10, 8, v10
	v_and_b32_e32 v13, 4, v13
	v_or3_b32 v8, v8, v10, v13
	s_movk_i32 s10, 0x90
	v_lshlrev_b64 v[2:3], 1, v[2:3]
	v_mad_u32_u24 v117, v8, s10, 0
	v_lshrrev_b32_e32 v8, 2, v6
	v_lshl_add_u64 v[106:107], s[44:45], 0, v[2:3]
	v_lshl_add_u64 v[110:111], s[42:43], 0, v[2:3]
	v_mul_lo_u32 v2, v7, s10
	v_and_b32_e32 v8, 11, v8
	s_movk_i32 s2, 0xc0
	v_add_u32_e32 v114, 0, v2
	v_mul_lo_u32 v2, v11, s10
	v_mad_u32_u24 v103, v8, s2, 0
	v_and_b32_e32 v8, 16, v6
	v_lshlrev_b32_e32 v6, 2, v6
	v_add_u32_e32 v116, 0, v2
	s_lshl_b32 s46, s4, 6
	s_and_b32 s4, s15, 0x1f00
	v_and_or_b32 v6, v6, 12, v8
	v_lshlrev_b64 v[4:5], 1, v[4:5]
	v_lshlrev_b32_e32 v120, 4, v9
	v_lshlrev_b32_e32 v121, 4, v12
	v_mad_u64_u32 v[16:17], s[10:11], v7, 48, v[114:115]
	v_mad_u64_u32 v[18:19], s[10:11], v11, 48, v[116:117]
	v_add_u32_e32 v2, s5, v1
	v_sub_u32_e32 v1, v100, v1
	v_mov_b32_e32 v14, v0
	v_mov_b32_e32 v15, v0
	v_lshlrev_b32_e32 v105, 1, v6
	v_lshl_add_u64 v[108:109], s[44:45], 0, v[4:5]
	v_lshl_add_u64 v[112:113], s[42:43], 0, v[4:5]
	v_add_u32_e32 v122, s4, v11
	v_add_u32_e32 v123, s4, v7
	v_sub_u32_e32 v124, v2, v100
	v_subrev_u32_e32 v125, s5, v1
	v_mov_b32_e32 v1, v0
	v_mov_b32_e32 v2, v0
	v_mov_b32_e32 v3, v0
	v_mov_b32_e32 v4, v0
	v_mov_b32_e32 v5, v0
	v_mov_b32_e32 v6, v0
	v_mov_b32_e32 v7, v0
	v_mov_b32_e32 v8, v0
	v_mov_b32_e32 v9, v0
	v_mov_b32_e32 v10, v0
	v_mov_b32_e32 v11, v0
	v_mov_b32_e32 v12, v0
	v_mov_b32_e32 v13, v0
	v_add_u32_e32 v118, v16, v120
	v_add_u32_e32 v119, v18, v121
	v_mov_b64_e32 v[30:31], v[14:15]
	v_mov_b64_e32 v[46:47], v[14:15]
	v_cndmask_b32_e64 v101, 0, 1.0, vcc
	s_add_i32 s53, s22, 0xffffff80
	s_add_i32 s52, s22, 0x9f
	s_add_i32 s49, s22, 0xffffff9f
	s_add_i32 s47, s22, 0x61
	s_mov_b32 s5, 0
	s_mov_b32 s22, 0
	v_mov_b64_e32 v[28:29], v[12:13]
	v_mov_b64_e32 v[26:27], v[10:11]
	v_mov_b64_e32 v[24:25], v[8:9]
	v_mov_b64_e32 v[22:23], v[6:7]
	v_mov_b64_e32 v[20:21], v[4:5]
	v_mov_b64_e32 v[18:19], v[2:3]
	v_mov_b64_e32 v[16:17], v[0:1]
	v_mov_b64_e32 v[44:45], v[12:13]
	v_mov_b64_e32 v[42:43], v[10:11]
	v_mov_b64_e32 v[40:41], v[8:9]
	v_mov_b64_e32 v[38:39], v[6:7]
	v_mov_b64_e32 v[36:37], v[4:5]
	v_mov_b64_e32 v[34:35], v[2:3]
	v_mov_b64_e32 v[32:33], v[0:1]
	v_add_u32_e32 v176, s5, v123
	v_add_u32_e32 v177, s5, v122
	v_cmp_gt_u32_e32 vcc, s31, v176
	v_cndmask_b32_e32 v176, 0, v176, vcc
	v_or_b32_e32 v176, s26, v176
	v_cmp_gt_u32_e32 vcc, s31, v177
	v_cndmask_b32_e32 v177, 0, v177, vcc
	v_or_b32_e32 v177, s26, v177
	v_mad_u64_u32 v[178:179], s[10:11], v176, s38, v[106:107]
	v_mad_i32_i24 v179, s27, v235, v179
	global_load_dwordx4 v[160:163], v[178:179], off
	v_mad_u64_u32 v[180:181], s[10:11], v177, s38, v[108:109]
	v_mad_i32_i24 v181, s27, v235, v181
	global_load_dwordx4 v[164:167], v[180:181], off
	v_mad_u64_u32 v[178:179], s[10:11], v176, s38, v[110:111]
	v_mad_i32_i24 v179, s27, v235, v179
	global_load_dwordx4 v[168:171], v[178:179], off
	v_mad_u64_u32 v[180:181], s[10:11], v177, s38, v[112:113]
	v_mad_i32_i24 v181, s27, v235, v181
	global_load_dwordx4 v[172:175], v[180:181], off
	s_branch .LBB0_171

; #define LAS __attribute__((address_space(3)))
; template <int HD, int DV, int HW, int MODE> ...
;     ...
;     for (int c = 0; c < NC; ++c) {
;         const int jc = i0 - HW + CR * c;
;         __syncthreads();
; #pragma unroll
;         for (int i = 0; i < KLD; ++i) { const int idx = tid + 512 * i, row = idx / KCH, ch = idx % KCH; *(LAS u32x4*)(Kl + row * RSK + ch * 16) = kreg[i]; }
; #pragma unroll
;         for (int i = 0; i < VLD; ++i) { const int idx = tid + 512 * i, row = idx / VCH, ch = idx % VCH; *(LAS u32x4*)(Vl + row * RSV + ch * 16) = vreg[i]; }
;         __syncthreads();
;         if (c + 1 < NC) prefetch(c + 1);
; #pragma unroll
;         for (int u = 0; u < CR / 32; ++u) {
;             const int js = jc + 32 * u;
;             if (js + 31 < iw - HW || js > iw + 31 + HW || js + 31 < 0 || js >= L) continue;
;             f32x16 S;
; #pragma unroll
;             for (int i = 0; i < 16; ++i) S[i] = 0.f;
; #pragma unroll
;             for (int ks = 0; ks < KS; ++ks) { const bf16x8 kf = *(const LAS bf16x8*)(kread + (32 * u) * RSK + 32 * ks); S = __builtin_amdgcn_mfma_f32_32x32x16_bf16(kf, qf[ks], S, 0, 0, 0); }
.LBB0_170:
	s_addk_i32 s22, 0xff80
	s_addk_i32 s5, 0x80
	s_cmpk_lg_i32 s22, 0xfe80
	s_cbranch_scc0 .LBB0_210
	s_branch .LswB_171
.LBB0_171:
	v_add_u32_e32 v1, v114, v120
	v_add_u32_e32 v2, v116, v121
	s_barrier
	s_waitcnt vmcnt(4)
	v_add_u32_e32 v176, s5, v123
	v_add_u32_e32 v177, s5, v122
	v_add_u32_e32 v176, 0xffffff80, v176
	v_add_u32_e32 v177, 0xffffff80, v177
	v_cmp_gt_u32_e32 vcc, s31, v176
	v_cndmask_b32_e32 v84, 0, v84, vcc
	v_cndmask_b32_e32 v85, 0, v85, vcc
	v_cndmask_b32_e32 v86, 0, v86, vcc
	v_cndmask_b32_e32 v87, 0, v87, vcc
	v_cndmask_b32_e32 v88, 0, v88, vcc
	v_cndmask_b32_e32 v89, 0, v89, vcc
	v_cndmask_b32_e32 v90, 0, v90, vcc
	v_cndmask_b32_e32 v91, 0, v91, vcc
	v_cmp_gt_u32_e32 vcc, s31, v177
	v_cndmask_b32_e32 v80, 0, v80, vcc
	v_cndmask_b32_e32 v81, 0, v81, vcc
	v_cndmask_b32_e32 v82, 0, v82, vcc
	v_cndmask_b32_e32 v83, 0, v83, vcc
	v_cndmask_b32_e32 v92, 0, v92, vcc
	v_cndmask_b32_e32 v93, 0, v93, vcc
	v_cndmask_b32_e32 v94, 0, v94, vcc
	v_cndmask_b32_e32 v95, 0, v95, vcc
	ds_write_b128 v1, v[84:87]
	ds_write_b128 v2, v[80:83]
	ds_write_b128 v118, v[88:91] offset:18432
	ds_write_b128 v119, v[92:95] offset:18432
	s_waitcnt lgkmcnt(0)
	s_barrier
	s_cmp_lg_u32 s5, 0
	s_cbranch_scc1 .LswA_nopf
	v_add_u32_e32 v176, s5, v123
	v_add_u32_e32 v177, s5, v122
	v_add_u32_e32 v176, 0x80, v176
	v_add_u32_e32 v177, 0x80, v177
	v_cmp_gt_u32_e32 vcc, s31, v176
	v_cndmask_b32_e32 v176, 0, v176, vcc
	v_or_b32_e32 v176, s26, v176
	v_cmp_gt_u32_e32 vcc, s31, v177
	v_cndmask_b32_e32 v177, 0, v177, vcc
	v_or_b32_e32 v177, s26, v177
	v_mad_u64_u32 v[178:179], s[10:11], v176, s38, v[106:107]
	v_mad_i32_i24 v179, s27, v235, v179
	global_load_dwordx4 v[84:87], v[178:179], off
	v_mad_u64_u32 v[180:181], s[10:11], v177, s38, v[108:109]
	v_mad_i32_i24 v181, s27, v235, v181
	global_load_dwordx4 v[80:83], v[180:181], off
	v_mad_u64_u32 v[178:179], s[10:11], v176, s38, v[110:111]
	v_mad_i32_i24 v179, s27, v235, v179
	global_load_dwordx4 v[88:91], v[178:179], off
	v_mad_u64_u32 v[180:181], s[10:11], v177, s38, v[112:113]
	v_mad_i32_i24 v181, s27, v235, v181
	global_load_dwordx4 v[92:95], v[180:181], off
.LswA_nopf:
	s_add_i32 s25, s4, s5
	s_add_i32 s23, s25, 0xffffff80
	s_add_i32 s2, s25, 0xffffff9f
	s_cmp_lt_i32 s2, s53
	s_cselect_b64 s[10:11], -1, 0
	s_cmp_gt_i32 s23, s52
	s_cselect_b64 s[28:29], -1, 0
	s_or_b64 s[10:11], s[10:11], s[28:29]
	s_cmpk_gt_u32 s2, 0x201e
	s_cselect_b64 s[28:29], -1, 0
	s_or_b64 s[10:11], s[28:29], s[10:11]
	s_and_b64 vcc, exec, s[10:11]
	s_cbranch_vccnz .LBB0_187
	v_add_u32_e32 v3, v117, v102
	ds_read_b128 v[4:7], v3
	ds_read_b128 v[126:129], v3 offset:32
	ds_read_b128 v[130:133], v3 offset:64
	ds_read_b128 v[134:137], v3 offset:96
	s_cmp_lt_i32 s23, s49
	s_cselect_b64 s[40:41], -1, 0
	s_and_b64 vcc, exec, s[40:41]
	s_waitcnt lgkmcnt(3)
	v_mfma_f32_32x32x16_bf16 v[48:63], v[4:7], v[76:79], 0
	s_waitcnt lgkmcnt(2)
	v_mfma_f32_32x32x16_bf16 v[48:63], v[126:129], v[72:75], v[48:63]
	s_waitcnt lgkmcnt(1)
	v_mfma_f32_32x32x16_bf16 v[48:63], v[130:133], v[68:71], v[48:63]
	s_waitcnt lgkmcnt(0)
	v_mfma_f32_32x32x16_bf16 v[48:63], v[134:137], v[64:67], v[48:63]
	v_add_u32_e32 v154, v103, v105
	ds_read_b64_tr_b16 v[138:139], v154 offset:18432
	ds_read_b64_tr_b16 v[140:141], v154 offset:19200
	ds_read_b64_tr_b16 v[142:143], v154 offset:21504
	ds_read_b64_tr_b16 v[144:145], v154 offset:22272
	ds_read_b64_tr_b16 v[146:147], v154 offset:18496
	ds_read_b64_tr_b16 v[148:149], v154 offset:19264
	ds_read_b64_tr_b16 v[150:151], v154 offset:21568
	ds_read_b64_tr_b16 v[152:153], v154 offset:22336
	s_cbranch_vccnz .LBB0_182
	s_cmp_gt_i32 s23, s47
	s_cselect_b64 s[10:11], -1, 0
	s_cmpk_gt_u32 s23, 0x1fe0
	s_cselect_b64 s[28:29], -1, 0
	s_or_b64 s[40:41], s[10:11], s[28:29]

; #define LAS __attribute__((address_space(3)))
; __device__ __forceinline__ float xmax32(float v) { const auto r = __builtin_amdgcn_permlane32_swap(__float_as_uint(v), __float_as_uint(v), false, false); return __builtin_fmaxf(__uint_as_float(r[0]), __uint_as_float(r[1])); }
; template <int HD, int DV, int HW, int MODE> ...
;     ...
;             float mt = xmax32(max16(S));
;             if (__any(mt > m + 8.0f)) {
;                 const float mn = fmaxf(m, mt), a = __builtin_amdgcn_exp2f(m - mn); l *= a; m = mn;
; #pragma unroll
;                 for (int t = 0; t < NTV; ++t) O[t] = O[t] * a;
;             }
; #pragma unroll
;             for (int i = 0; i < 16; ++i) S[i] = __builtin_amdgcn_exp2f(S[i] - m);
;             l += sum16(S);
;             const bf16x8 P0 = pack8(S, 0), P1 = pack8(S, 8);
; #pragma unroll
;             for (int t = 0; t < NTV; ++t) {
;                 const LAS unsigned char* vb = vread + (32 * u) * RSV + 64 * t;
;                 const bf16x8 v0 = tr_pair(vb, vb + 4 * RSV), v1 = tr_pair(vb + 16 * RSV, vb + 20 * RSV);
;                 O[t] = __builtin_amdgcn_mfma_f32_32x32x16_bf16(v0, P0, O[t], 0, 0, 0);
;                 O[t] = __builtin_amdgcn_mfma_f32_32x32x16_bf16(v1, P1, O[t], 0, 0, 0);
;             }
.LBB0_208:
	s_nop 3
	v_max3_f32 v3, v48, v49, v50
	v_max3_f32 v4, v51, v52, v53
	v_max3_f32 v3, v3, v54, v55
	v_max3_f32 v4, v4, v56, v57
	v_max_f32_e32 v5, v63, v63
	v_max_f32_e32 v6, v62, v62
	v_max3_f32 v3, v3, v58, v59
	v_max3_f32 v4, v4, v60, v61
	v_max_f32_e32 v5, v6, v5
	v_max3_f32 v3, v3, v4, v5
	v_mov_b32_e32 v4, v3
	s_nop 1
	v_permlane32_swap_b32_e32 v3, v4
	v_max_f32_e32 v4, v4, v4
	v_max_f32_e32 v3, v3, v3
	v_max_f32_e32 v3, v3, v4
	v_add_f32_e32 v4, 0x41000000, v115
	v_cmp_gt_f32_e32 vcc, v3, v4
	s_cbranch_vccz .LBB0_169
	v_max_f32_e32 v3, v3, v3
	v_max_f32_e32 v4, v115, v115
	v_max_f32_e32 v3, v4, v3
	v_sub_f32_e32 v4, v115, v3
	v_exp_f32_e32 v4, v4
	v_mov_b32_e32 v115, v3
	v_pk_mul_f32 v[46:47], v[46:47], v[4:5] op_sel_hi:[1,0]
	v_pk_mul_f32 v[44:45], v[44:45], v[4:5] op_sel_hi:[1,0]
	v_pk_mul_f32 v[42:43], v[42:43], v[4:5] op_sel_hi:[1,0]
	v_pk_mul_f32 v[40:41], v[40:41], v[4:5] op_sel_hi:[1,0]
	v_pk_mul_f32 v[38:39], v[38:39], v[4:5] op_sel_hi:[1,0]
	v_pk_mul_f32 v[36:37], v[36:37], v[4:5] op_sel_hi:[1,0]
	v_pk_mul_f32 v[34:35], v[34:35], v[4:5] op_sel_hi:[1,0]
	v_pk_mul_f32 v[32:33], v[32:33], v[4:5] op_sel_hi:[1,0]
	v_pk_mul_f32 v[30:31], v[30:31], v[4:5] op_sel_hi:[1,0]
	v_pk_mul_f32 v[28:29], v[28:29], v[4:5] op_sel_hi:[1,0]
	v_pk_mul_f32 v[26:27], v[26:27], v[4:5] op_sel_hi:[1,0]
	v_pk_mul_f32 v[24:25], v[24:25], v[4:5] op_sel_hi:[1,0]
	v_pk_mul_f32 v[22:23], v[22:23], v[4:5] op_sel_hi:[1,0]
	v_pk_mul_f32 v[20:21], v[20:21], v[4:5] op_sel_hi:[1,0]
	v_pk_mul_f32 v[18:19], v[18:19], v[4:5] op_sel_hi:[1,0]
	v_pk_mul_f32 v[16:17], v[16:17], v[4:5] op_sel_hi:[1,0]
	v_mul_f32_e32 v101, v101, v4
	s_branch .LBB0_169
.LswB_169:
	v_sub_f32_e32 v3, v48, v115
	v_exp_f32_e32 v8, v3
	v_sub_f32_e32 v3, v49, v115
	v_exp_f32_e32 v10, v3
	v_sub_f32_e32 v3, v50, v115
	v_exp_f32_e32 v12, v3
	v_sub_f32_e32 v3, v51, v115
	v_exp_f32_e32 v14, v3
	v_sub_f32_e32 v3, v52, v115
	v_exp_f32_e32 v48, v3
	v_sub_f32_e32 v3, v53, v115
	v_exp_f32_e32 v50, v3
	v_sub_f32_e32 v3, v54, v115
	v_exp_f32_e32 v52, v3
	v_sub_f32_e32 v3, v55, v115
	v_exp_f32_e32 v54, v3
	v_sub_f32_e32 v3, v56, v115
	v_exp_f32_e32 v9, v3
	v_sub_f32_e32 v3, v57, v115
	v_exp_f32_e32 v11, v3
	v_sub_f32_e32 v3, v58, v115
	v_exp_f32_e32 v13, v3
	v_sub_f32_e32 v3, v59, v115
	v_exp_f32_e32 v15, v3
	v_sub_f32_e32 v3, v60, v115
	v_exp_f32_e32 v49, v3
	v_sub_f32_e32 v3, v61, v115
	v_exp_f32_e32 v51, v3
	v_sub_f32_e32 v3, v62, v115
	v_exp_f32_e32 v53, v3
	v_sub_f32_e32 v3, v63, v115
	v_exp_f32_e32 v55, v3
	v_pk_add_f32 v[4:5], v[8:9], v[10:11]
	v_pk_add_f32 v[6:7], v[12:13], v[14:15]
	v_pk_add_f32 v[56:57], v[52:53], v[54:55]
	v_pk_add_f32 v[4:5], v[4:5], v[6:7]
	v_pk_add_f32 v[6:7], v[48:49], v[50:51]
	s_nop 0
	v_pk_add_f32 v[6:7], v[6:7], v[56:57]
	s_nop 0
	v_pk_add_f32 v[4:5], v[4:5], v[6:7]
	v_cvt_pk_bf16_f32 v7, v52, v54
	v_add_u32_e32 v52, v103, v105
	v_add_f32_e32 v3, v4, v5
	v_cvt_pk_bf16_f32 v4, v8, v10
	v_cvt_pk_bf16_f32 v5, v12, v14
	v_cvt_pk_bf16_f32 v6, v48, v50
	v_cvt_pk_bf16_f32 v8, v9, v11
	v_cvt_pk_bf16_f32 v9, v13, v15
	v_cvt_pk_bf16_f32 v10, v49, v51
	s_waitcnt lgkmcnt(6)
	v_mfma_f32_32x32x16_bf16 v[32:47], v[138:141], v[4:7], v[32:47]
	v_cvt_pk_bf16_f32 v11, v53, v55
	v_add_f32_e32 v101, v101, v3
	s_waitcnt lgkmcnt(4)
	v_mfma_f32_32x32x16_bf16 v[32:47], v[142:145], v[8:11], v[32:47]
	s_waitcnt lgkmcnt(2)
	v_mfma_f32_32x32x16_bf16 v[16:31], v[146:149], v[4:7], v[16:31]
	s_waitcnt lgkmcnt(0)
	v_mfma_f32_32x32x16_bf16 v[16:31], v[150:153], v[8:11], v[16:31]
.LswB_170:
	s_addk_i32 s22, 0xff80
	s_addk_i32 s5, 0x80
	s_branch .LBB0_171
; #define LAS __attribute__((address_space(3)))
; template <int HD, int DV, int HW, int MODE> ...
;     ...
;     for (int c = 0; c < NC; ++c) {
;         const int jc = i0 - HW + CR * c;
;         __syncthreads();
; #pragma unroll
;         for (int i = 0; i < KLD; ++i) { const int idx = tid + 512 * i, row = idx / KCH, ch = idx % KCH; *(LAS u32x4*)(Kl + row * RSK + ch * 16) = kreg[i]; }
; #pragma unroll
;         for (int i = 0; i < VLD; ++i) { const int idx = tid + 512 * i, row = idx / VCH, ch = idx % VCH; *(LAS u32x4*)(Vl + row * RSV + ch * 16) = vreg[i]; }
;         __syncthreads();
;         if (c + 1 < NC) prefetch(c + 1);
; #pragma unroll
;         for (int u = 0; u < CR / 32; ++u) {
;             const int js = jc + 32 * u;
;             if (js + 31 < iw - HW || js > iw + 31 + HW || js + 31 < 0 || js >= L) continue;
;             f32x16 S;
; #pragma unroll
;             for (int i = 0; i < 16; ++i) S[i] = 0.f;
; #pragma unroll
;             for (int ks = 0; ks < KS; ++ks) { const bf16x8 kf = *(const LAS bf16x8*)(kread + (32 * u) * RSK + 32 * ks); S = __builtin_amdgcn_mfma_f32_32x32x16_bf16(kf, qf[ks], S, 0, 0, 0); }
.LswB_171:
	v_add_u32_e32 v1, v114, v120
	v_add_u32_e32 v2, v116, v121
	s_barrier
	s_waitcnt vmcnt(4)
	v_add_u32_e32 v176, s5, v123
	v_add_u32_e32 v177, s5, v122
	v_add_u32_e32 v176, 0xffffff80, v176
	v_add_u32_e32 v177, 0xffffff80, v177
	v_cmp_gt_u32_e32 vcc, s31, v176
	v_cndmask_b32_e32 v160, 0, v160, vcc
	v_cndmask_b32_e32 v161, 0, v161, vcc
	v_cndmask_b32_e32 v162, 0, v162, vcc
	v_cndmask_b32_e32 v163, 0, v163, vcc
	v_cndmask_b32_e32 v168, 0, v168, vcc
	v_cndmask_b32_e32 v169, 0, v169, vcc
	v_cndmask_b32_e32 v170, 0, v170, vcc
	v_cndmask_b32_e32 v171, 0, v171, vcc
	v_cmp_gt_u32_e32 vcc, s31, v177
	v_cndmask_b32_e32 v164, 0, v164, vcc
	v_cndmask_b32_e32 v165, 0, v165, vcc
	v_cndmask_b32_e32 v166, 0, v166, vcc
	v_cndmask_b32_e32 v167, 0, v167, vcc
	v_cndmask_b32_e32 v172, 0, v172, vcc
	v_cndmask_b32_e32 v173, 0, v173, vcc
	v_cndmask_b32_e32 v174, 0, v174, vcc
	v_cndmask_b32_e32 v175, 0, v175, vcc
	ds_write_b128 v1, v[160:163]
	ds_write_b128 v2, v[164:167]
	ds_write_b128 v118, v[168:171] offset:18432
	ds_write_b128 v119, v[172:175] offset:18432
	s_waitcnt lgkmcnt(0)
	s_barrier
	v_add_u32_e32 v176, s5, v123
	v_add_u32_e32 v177, s5, v122
	v_add_u32_e32 v176, 0x80, v176
	v_add_u32_e32 v177, 0x80, v177
	v_cmp_gt_u32_e32 vcc, s31, v176
	v_cndmask_b32_e32 v176, 0, v176, vcc
	v_or_b32_e32 v176, s26, v176
	v_cmp_gt_u32_e32 vcc, s31, v177
	v_cndmask_b32_e32 v177, 0, v177, vcc
	v_or_b32_e32 v177, s26, v177
	v_mad_u64_u32 v[178:179], s[10:11], v176, s38, v[106:107]
	v_mad_i32_i24 v179, s27, v235, v179
	global_load_dwordx4 v[160:163], v[178:179], off
	v_mad_u64_u32 v[180:181], s[10:11], v177, s38, v[108:109]
	v_mad_i32_i24 v181, s27, v235, v181
	global_load_dwordx4 v[164:167], v[180:181], off
	v_mad_u64_u32 v[178:179], s[10:11], v176, s38, v[110:111]
	v_mad_i32_i24 v179, s27, v235, v179
	global_load_dwordx4 v[168:171], v[178:179], off
	v_mad_u64_u32 v[180:181], s[10:11], v177, s38, v[112:113]
	v_mad_i32_i24 v181, s27, v235, v181
	global_load_dwordx4 v[172:175], v[180:181], off
	s_add_i32 s25, s4, s5
	s_add_i32 s23, s25, 0xffffff80
	s_add_i32 s2, s25, 0xffffff9f
	s_cmp_lt_i32 s2, s53
	s_cselect_b64 s[10:11], -1, 0
	s_cmp_gt_i32 s23, s52
	s_cselect_b64 s[28:29], -1, 0
	s_or_b64 s[10:11], s[10:11], s[28:29]
	s_cmpk_gt_u32 s2, 0x201e
	s_cselect_b64 s[28:29], -1, 0
	s_or_b64 s[10:11], s[28:29], s[10:11]
	s_and_b64 vcc, exec, s[10:11]
	s_cbranch_vccnz .LswB_187
	v_add_u32_e32 v3, v117, v102
	ds_read_b128 v[4:7], v3
	ds_read_b128 v[126:129], v3 offset:32
	ds_read_b128 v[130:133], v3 offset:64
	ds_read_b128 v[134:137], v3 offset:96
	s_cmp_lt_i32 s23, s49
	s_cselect_b64 s[40:41], -1, 0
	s_and_b64 vcc, exec, s[40:41]
	s_waitcnt lgkmcnt(3)
	v_mfma_f32_32x32x16_bf16 v[48:63], v[4:7], v[76:79], 0
	s_waitcnt lgkmcnt(2)
	v_mfma_f32_32x32x16_bf16 v[48:63], v[126:129], v[72:75], v[48:63]
	s_waitcnt lgkmcnt(1)
	v_mfma_f32_32x32x16_bf16 v[48:63], v[130:133], v[68:71], v[48:63]
	s_waitcnt lgkmcnt(0)
	v_mfma_f32_32x32x16_bf16 v[48:63], v[134:137], v[64:67], v[48:63]
	v_add_u32_e32 v154, v103, v105
	ds_read_b64_tr_b16 v[138:139], v154 offset:18432
	ds_read_b64_tr_b16 v[140:141], v154 offset:19200
	ds_read_b64_tr_b16 v[142:143], v154 offset:21504
	ds_read_b64_tr_b16 v[144:145], v154 offset:22272
	ds_read_b64_tr_b16 v[146:147], v154 offset:18496
	ds_read_b64_tr_b16 v[148:149], v154 offset:19264
	ds_read_b64_tr_b16 v[150:151], v154 offset:21568
	ds_read_b64_tr_b16 v[152:153], v154 offset:22336
	s_cbranch_vccnz .LswB_182
	s_cmp_gt_i32 s23, s47
	s_cselect_b64 s[10:11], -1, 0
	s_cmpk_gt_u32 s23, 0x1fe0
	s_cselect_b64 s[28:29], -1, 0
	s_or_b64 s[40:41], s[10:11], s[28:29]

; #define LAS __attribute__((address_space(3)))
; template <int HD, int DV, int HW, int MODE> ...
;     ...
;     for (int c = 0; c < NC; ++c) {
;         const int jc = i0 - HW + CR * c;
;         __syncthreads();
; #pragma unroll
;         for (int i = 0; i < KLD; ++i) { const int idx = tid + 512 * i, row = idx / KCH, ch = idx % KCH; *(LAS u32x4*)(Kl + row * RSK + ch * 16) = kreg[i]; }
; #pragma unroll
;         for (int i = 0; i < VLD; ++i) { const int idx = tid + 512 * i, row = idx / VCH, ch = idx % VCH; *(LAS u32x4*)(Vl + row * RSV + ch * 16) = vreg[i]; }
;         __syncthreads();
;         if (c + 1 < NC) prefetch(c + 1);
; #pragma unroll
;         for (int u = 0; u < CR / 32; ++u) {
;             const int js = jc + 32 * u;
;             if (js + 31 < iw - HW || js > iw + 31 + HW || js + 31 < 0 || js >= L) continue;
;             f32x16 S;
; #pragma unroll
;             for (int i = 0; i < 16; ++i) S[i] = 0.f;
; #pragma unroll
;             for (int ks = 0; ks < KS; ++ks) { const bf16x8 kf = *(const LAS bf16x8*)(kread + (32 * u) * RSK + 32 * ks); S = __builtin_amdgcn_mfma_f32_32x32x16_bf16(kf, qf[ks], S, 0, 0, 0); }
.LBB0_210:
	s_add_i32 s4, s48, 0x100
	s_add_i32 s2, s48, 0x11f
	s_cmp_lt_i32 s2, s53
	s_cselect_b64 s[10:11], -1, 0
	s_cmp_gt_i32 s4, s52
	s_cselect_b64 s[22:23], -1, 0
	s_or_b64 s[10:11], s[10:11], s[22:23]
	s_cmpk_gt_u32 s2, 0x201e
	s_cselect_b64 s[22:23], -1, 0
	s_or_b64 s[10:11], s[22:23], s[10:11]
	v_add_u32_e32 v107, 0x80, v104
	v_add_u32_e32 v106, 0x7e, v104
	v_add_u32_e32 v15, 0x7d, v104
	v_add_u32_e32 v14, 0x7c, v104
	v_add_u32_e32 v13, 0x7b, v104
	v_add_u32_e32 v12, 0x7a, v104
	v_add_u32_e32 v11, 0x79, v104
	v_add_u32_e32 v10, 0x70, v104
	v_add_u32_e32 v9, 0x6f, v104
	v_add_u32_e32 v8, 0x6e, v104
	v_add_u32_e32 v7, 0x6d, v104
	v_add_u32_e32 v6, 0x6c, v104
	v_add_u32_e32 v5, 0x6b, v104
	v_add_u32_e32 v4, 0x6a, v104
	v_add_u32_e32 v3, 0x69, v104
	s_barrier
	s_waitcnt vmcnt(0)
	v_add_u32_e32 v176, s5, v123
	v_add_u32_e32 v177, s5, v122
	v_add_u32_e32 v176, 0xffffff80, v176
	v_add_u32_e32 v177, 0xffffff80, v177
	v_cmp_gt_u32_e32 vcc, s31, v176
	v_cndmask_b32_e32 v160, 0, v160, vcc
	v_cndmask_b32_e32 v161, 0, v161, vcc
	v_cndmask_b32_e32 v162, 0, v162, vcc
	v_cndmask_b32_e32 v163, 0, v163, vcc
	v_cndmask_b32_e32 v168, 0, v168, vcc
	v_cndmask_b32_e32 v169, 0, v169, vcc
	v_cndmask_b32_e32 v170, 0, v170, vcc
	v_cndmask_b32_e32 v171, 0, v171, vcc
	v_cmp_gt_u32_e32 vcc, s31, v177
	v_cndmask_b32_e32 v164, 0, v164, vcc
	v_cndmask_b32_e32 v165, 0, v165, vcc
	v_cndmask_b32_e32 v166, 0, v166, vcc
	v_cndmask_b32_e32 v167, 0, v167, vcc
	v_cndmask_b32_e32 v172, 0, v172, vcc
	v_cndmask_b32_e32 v173, 0, v173, vcc
	v_cndmask_b32_e32 v174, 0, v174, vcc
	v_cndmask_b32_e32 v175, 0, v175, vcc
	ds_write_b128 v1, v[160:163]
	ds_write_b128 v2, v[164:167]
	ds_write_b128 v118, v[168:171] offset:18432
	ds_write_b128 v119, v[172:175] offset:18432
	s_and_b64 vcc, exec, s[10:11]
	v_add_u32_e32 v1, v117, v102
	s_waitcnt lgkmcnt(0)
	s_barrier
	s_cbranch_vccnz .LBB0_218
	ds_read_b128 v[48:51], v1
	ds_read_b128 v[80:83], v1 offset:32
	ds_read_b128 v[126:129], v1 offset:64
	ds_read_b128 v[130:133], v1 offset:96
	s_cmp_lt_i32 s4, s49
	s_cselect_b64 s[26:27], -1, 0
	s_and_b64 vcc, exec, s[26:27]
	s_waitcnt lgkmcnt(3)
	v_mfma_f32_32x32x16_bf16 v[48:63], v[48:51], v[76:79], 0
	s_waitcnt lgkmcnt(2)
	v_mfma_f32_32x32x16_bf16 v[48:63], v[80:83], v[72:75], v[48:63]
	s_waitcnt lgkmcnt(1)
	v_mfma_f32_32x32x16_bf16 v[48:63], v[126:129], v[68:71], v[48:63]
	s_waitcnt lgkmcnt(0)
	v_mfma_f32_32x32x16_bf16 v[48:63], v[130:133], v[64:67], v[48:63]
	v_add_u32_e32 v154, v103, v105
	ds_read_b64_tr_b16 v[138:139], v154 offset:18432
	ds_read_b64_tr_b16 v[140:141], v154 offset:19200
	ds_read_b64_tr_b16 v[142:143], v154 offset:21504
	ds_read_b64_tr_b16 v[144:145], v154 offset:22272
	ds_read_b64_tr_b16 v[146:147], v154 offset:18496
	ds_read_b64_tr_b16 v[148:149], v154 offset:19264
	ds_read_b64_tr_b16 v[150:151], v154 offset:21568
	ds_read_b64_tr_b16 v[152:153], v154 offset:22336
	s_cbranch_vccnz .LBB0_213
	s_cmp_gt_i32 s4, s47
	s_cselect_b64 s[10:11], -1, 0
	s_cmpk_gt_u32 s48, 0x1ee0
	s_cselect_b64 s[22:23], -1, 0
	s_or_b64 s[26:27], s[10:11], s[22:23]
